# GLA prep gate loop: distance-1 software prefetch of the per-token gate rows
# baseline (speedup 1.0000x reference)
; __global__ void __launch_bounds__(NTHR) mega(Params p) {
;     ...
;         for (int it = blockIdx.x; it < 2048; it += gridDim.x) {
;           const int b = it >> 9, n = (it >> 2) & 127, hh = it & 3;
;           const size_t tok0 = (size_t)b * SEQ + n * 64;
;           const int c = tid & 127, tg = tid >> 7;
;           {
;             float w[16];
; #pragma unroll
;             for (int j = 0; j < 16; ++j) w[j] = w2[j * 512 + hh * 128 + c];
;             const float bias = gb[hh * 128 + c];
;             for (int tt = 0; tt < 16; ++tt) {
;               const int t = tg * 16 + tt;
;               const uint4 g0 = *(const uint4*)(GL + (tok0 + t) * 16);
.LBB0_2665:
	s_and_b32 s9, s8, 3
	s_lshl_b32 s74, s9, 7
	v_or_b32_e32 v0, s74, v18
	v_lshlrev_b32_e32 v0, 2, v0
	v_lshl_add_u64 v[10:11], s[96:97], 0, v[0:1]
	s_movk_i32 s10, 0x1000
	v_add_co_u32_e32 v8, vcc, s10, v10
	s_movk_i32 s10, 0x2000
	s_nop 0
	v_addc_co_u32_e32 v9, vcc, 0, v11, vcc
	v_add_co_u32_e32 v12, vcc, s10, v10
	s_movk_i32 s10, 0x3000
	s_nop 0
	v_addc_co_u32_e32 v13, vcc, 0, v11, vcc
	v_add_co_u32_e32 v14, vcc, s10, v10
	s_movk_i32 s10, 0x6000
	s_nop 0
	v_addc_co_u32_e32 v15, vcc, 0, v11, vcc
	flat_load_dword v2, v[10:11]
	flat_load_dword v4, v[10:11] offset:2048
	flat_load_dword v6, v[8:9]
	s_nop 0
	flat_load_dword v8, v[8:9] offset:2048
	s_nop 0
	flat_load_dword v3, v[12:13]
	flat_load_dword v5, v[12:13] offset:2048
	flat_load_dword v7, v[14:15]
	flat_load_dword v9, v[14:15] offset:2048
	v_add_co_u32_e32 v12, vcc, s72, v10
	s_ashr_i32 s94, s8, 9
	s_nop 0
	v_addc_co_u32_e32 v13, vcc, 0, v11, vcc
	v_add_co_u32_e32 v16, vcc, s58, v10
	s_ashr_i32 s95, s94, 31
	s_nop 0
	v_addc_co_u32_e32 v17, vcc, 0, v11, vcc
	v_add_co_u32_e32 v92, vcc, s10, v10
	s_movk_i32 s10, 0x7000
	s_nop 0
	v_addc_co_u32_e32 v93, vcc, 0, v11, vcc
	v_add_co_u32_e32 v130, vcc, s10, v10
	s_lshl_b32 s10, s8, 4
	s_nop 0
	v_addc_co_u32_e32 v131, vcc, 0, v11, vcc
	flat_load_dword v10, v[12:13]
	s_nop 0
	flat_load_dword v12, v[12:13] offset:2048
	s_nop 0
	flat_load_dword v14, v[16:17]
	s_nop 0
	flat_load_dword v16, v[16:17] offset:2048
	s_nop 0
	flat_load_dword v11, v[92:93]
	flat_load_dword v13, v[92:93] offset:2048
	flat_load_dword v15, v[130:131]
	flat_load_dword v17, v[130:131] offset:2048
	v_lshl_add_u64 v[92:93], s[82:83], 0, v[0:1]
	flat_load_dword v0, v[92:93]
	s_and_b32 s10, s10, 0x1fc0
	s_lshl_b64 s[80:81], s[94:95], 13
	s_or_b32 vcc_lo, s80, s10
	s_mov_b32 vcc_hi, s81
	v_lshl_add_u64 v[92:93], vcc, 0, v[20:21]
	v_lshlrev_b64 v[92:93], 5, v[92:93]
	s_lshr_b32 s42, s8, 2
	s_mov_b32 s43, 0
	v_lshl_add_u64 v[92:93], s[92:93], 0, v[92:93]
	global_load_dwordx4 v[148:151], v[92:93], off
	global_load_dwordx4 v[152:155], v[92:93], off offset:16
	v_lshl_add_u64 v[92:93], v[92:93], 0, 32
; DI float bflo(unsigned u) { return __uint_as_float(u << 16); }
; DI float bfhi(unsigned u) { return __uint_as_float(u & 0xffff0000u); }
; __global__ void __launch_bounds__(NTHR) mega(Params p) {
;     ...
;             for (int tt = 0; tt < 16; ++tt) {
;               const int t = tg * 16 + tt;
;               const uint4 g0 = *(const uint4*)(GL + (tok0 + t) * 16);
;               const uint4 g1 = *(const uint4*)(GL + (tok0 + t) * 16 + 8);
;               float x = bias;
;               x += bflo(g0.x) * w[0] + bfhi(g0.x) * w[1] + bflo(g0.y) * w[2] + bfhi(g0.y) * w[3];
;               x += bflo(g0.z) * w[4] + bfhi(g0.z) * w[5] + bflo(g0.w) * w[6] + bfhi(g0.w) * w[7];
;               x += bflo(g1.x) * w[8] + bfhi(g1.x) * w[9] + bflo(g1.y) * w[10] + bfhi(g1.y) * w[11];
;               x += bflo(g1.z) * w[12] + bfhi(g1.z) * w[13] + bflo(g1.w) * w[14] + bfhi(g1.w) * w[15];
;               const float ls = fminf(x, 0.f) - log1pf(__expf(-fabsf(x)));
;               Gs[t * 128 + c] = ls * (1.f / 16.f);
;             }
.LBB0_2666:
	s_mov_b32 s10, 0xbfb8aa3b
	s_waitcnt vmcnt(0) lgkmcnt(0)
	v_mov_b64_e32 v[130:131], v[148:149]
	v_mov_b64_e32 v[132:133], v[150:151]
	v_mov_b64_e32 v[156:157], v[152:153]
	v_mov_b64_e32 v[158:159], v[154:155]
	global_load_dwordx4 v[148:151], v[92:93], off
	global_load_dwordx4 v[152:155], v[92:93], off offset:16
	v_lshl_add_u64 v[92:93], v[92:93], 0, 32
	v_and_b32_e32 v137, 0xffff0000, v132
	v_and_b32_e32 v136, 0xffff0000, v130
	v_lshlrev_b32_e32 v135, 16, v132
	v_lshlrev_b32_e32 v134, 16, v130
	v_pk_mul_f32 v[136:137], v[4:5], v[136:137]
	v_and_b32_e32 v132, 0xffff0000, v131
	v_pk_fma_f32 v[134:135], v[2:3], v[134:135], v[136:137]
	v_lshlrev_b32_e32 v137, 16, v133
	v_lshlrev_b32_e32 v136, 16, v131
	v_pk_fma_f32 v[134:135], v[6:7], v[136:137], v[134:135]
	v_and_b32_e32 v133, 0xffff0000, v133
	v_pk_fma_f32 v[130:131], v[8:9], v[132:133], v[134:135]
	s_nop 0
	v_add_f32_e32 v130, v0, v130
	v_add_f32_e32 v138, v130, v131
	v_mov_b64_e32 v[130:131], v[156:157]
	v_mov_b64_e32 v[132:133], v[158:159]
	v_and_b32_e32 v137, 0xffff0000, v132
	v_and_b32_e32 v136, 0xffff0000, v130
	v_lshlrev_b32_e32 v135, 16, v132
	v_lshlrev_b32_e32 v134, 16, v130
	v_pk_mul_f32 v[136:137], v[12:13], v[136:137]
	v_and_b32_e32 v132, 0xffff0000, v131
	v_pk_fma_f32 v[134:135], v[10:11], v[134:135], v[136:137]
	v_lshlrev_b32_e32 v137, 16, v133
	v_lshlrev_b32_e32 v136, 16, v131
	v_pk_fma_f32 v[134:135], v[14:15], v[136:137], v[134:135]
	v_and_b32_e32 v133, 0xffff0000, v133
	v_pk_fma_f32 v[130:131], v[16:17], v[132:133], v[134:135]
	s_nop 0
	v_add_f32_e32 v130, v138, v130
	v_add_f32_e32 v130, v130, v131
	v_min_f32_e32 v144, 0, v130
	v_mul_f32_e64 v130, |v130|, s10
	v_exp_f32_e32 v145, v130
	s_mov_b32 s10, 0x3f2aaaab
	v_add_f32_e32 v132, 1.0, v145
	v_add_f32_e32 v130, -1.0, v132
	v_sub_f32_e32 v131, v130, v132
	v_add_f32_e32 v131, 1.0, v131
	v_sub_f32_e32 v130, v145, v130
	v_add_f32_e32 v133, v130, v131
	v_frexp_mant_f32_e32 v130, v132
	v_cmp_gt_f32_e32 vcc, s10, v130
	v_cvt_f64_f32_e32 v[130:131], v132
	v_frexp_exp_i32_f64_e32 v130, v[130:131]
	v_subbrev_co_u32_e32 v138, vcc, 0, v130, vcc
	v_sub_u32_e32 v130, 0, v138
	v_ldexp_f32 v131, v132, v130
	v_add_f32_e32 v132, -1.0, v131
	v_add_f32_e32 v134, 1.0, v131
	v_ldexp_f32 v130, v133, v130
	v_add_f32_e32 v133, 1.0, v132
	v_add_f32_e32 v135, -1.0, v134
	v_sub_f32_e32 v133, v131, v133
	v_sub_f32_e32 v131, v131, v135
	v_add_f32_e32 v133, v130, v133
	v_add_f32_e32 v130, v130, v131
	v_add_f32_e32 v139, v134, v130
	v_rcp_f32_e32 v141, v139
	v_sub_f32_e32 v131, v139, v134
	v_sub_f32_e32 v140, v130, v131
	v_add_f32_e32 v131, v132, v133
	v_mul_f32_e32 v143, v131, v141
	v_sub_f32_e32 v130, v131, v132
	v_mul_f32_e32 v132, v139, v143
	v_fma_f32 v134, v143, v139, -v132
	v_fmac_f32_e32 v134, v143, v140
	v_sub_f32_e32 v142, v133, v130
	v_add_f32_e32 v130, v132, v134
	v_sub_f32_e32 v133, v131, v130
	v_pk_add_f32 v[136:137], v[130:131], v[132:133] neg_lo:[0,1] neg_hi:[0,1]
	v_mov_b32_e32 v135, v130
	v_pk_add_f32 v[130:131], v[136:137], v[134:135] neg_lo:[0,1] neg_hi:[0,1]
	s_mov_b32 s10, 0x3f317218
	v_add_f32_e32 v131, v142, v131
	v_add_f32_e32 v130, v130, v131
	v_add_f32_e32 v131, v133, v130
	v_mul_f32_e32 v142, v141, v131
	v_mul_f32_e32 v132, v139, v142
	v_fma_f32 v134, v142, v139, -v132
	v_fmac_f32_e32 v134, v142, v140
	v_sub_f32_e32 v133, v133, v131
	v_add_f32_e32 v139, v130, v133
	v_add_f32_e32 v130, v132, v134
	v_sub_f32_e32 v133, v131, v130
	v_pk_add_f32 v[136:137], v[130:131], v[132:133] neg_lo:[0,1] neg_hi:[0,1]
	v_mov_b32_e32 v135, v130
	v_pk_add_f32 v[130:131], v[136:137], v[134:135] neg_lo:[0,1] neg_hi:[0,1]
	v_cmp_neq_f32_e32 vcc, s65, v145
	v_add_f32_e32 v131, v139, v131
	v_add_f32_e32 v130, v130, v131
	v_add_f32_e32 v131, v143, v142
	v_add_f32_e32 v130, v133, v130
	v_sub_f32_e32 v132, v131, v143
	v_mul_f32_e32 v130, v141, v130
	v_sub_f32_e32 v132, v142, v132
	v_add_f32_e32 v132, v132, v130
	v_add_f32_e32 v134, v131, v132
	v_mul_f32_e32 v135, v134, v134
	v_mov_b32_e32 v130, 0x3ecc95a3
	v_fmamk_f32 v130, v135, 0x3e9b6dac, v130
	v_fmaak_f32 v175, v135, v130, 0x3f2aaada
	v_cvt_f32_i32_e32 v130, v138
	v_sub_f32_e32 v131, v134, v131
	v_sub_f32_e32 v131, v132, v131
	v_ldexp_f32 v136, v131, 1
	v_mul_f32_e32 v131, v134, v135
	v_ldexp_f32 v133, v134, 1
	v_pk_mul_f32 v[134:135], v[130:131], v[174:175]
	s_nop 0
	v_fma_f32 v132, v130, s10, -v134
	v_fmac_f32_e32 v132, 0xb102e308, v130
	v_pk_add_f32 v[130:131], v[134:135], v[132:133]
	s_mov_b32 s10, 0x33800000
	v_sub_f32_e32 v133, v131, v133
	v_sub_f32_e32 v133, v135, v133
	v_add_f32_e32 v137, v136, v133
	v_mov_b32_e32 v136, v134
	v_pk_add_f32 v[134:135], v[130:131], v[134:135] neg_lo:[0,1] neg_hi:[0,1]
	v_pk_add_f32 v[138:139], v[130:131], v[136:137]
	v_mov_b32_e32 v133, v130
	v_mov_b32_e32 v135, v139
	v_pk_add_f32 v[140:141], v[132:133], v[134:135] neg_lo:[0,1] neg_hi:[0,1]
	v_pk_add_f32 v[132:133], v[132:133], v[134:135]
	v_mov_b32_e32 v136, v137
	v_pk_add_f32 v[134:135], v[132:133], v[130:131] op_sel:[1,0] op_sel_hi:[0,1] neg_lo:[0,1] neg_hi:[0,1]
	v_pk_add_f32 v[142:143], v[138:139], v[134:135] op_sel_hi:[1,0] neg_lo:[0,1] neg_hi:[0,1]
	v_mov_b32_e32 v138, v139
	v_mov_b32_e32 v139, v133
	v_pk_mov_b32 v[134:135], v[130:131], v[134:135] op_sel:[1,0]
	v_mov_b32_e32 v137, v130
	v_pk_add_f32 v[134:135], v[138:139], v[134:135] neg_lo:[0,1] neg_hi:[0,1]
	v_mov_b32_e32 v142, v140
	v_pk_add_f32 v[130:131], v[136:137], v[134:135] neg_lo:[0,1] neg_hi:[0,1]
	v_mov_b32_e32 v141, v133
	v_pk_add_f32 v[134:135], v[142:143], v[130:131]
	s_nop 0
	v_pk_add_f32 v[136:137], v[134:135], v[134:135] op_sel:[0,1] op_sel_hi:[1,0]
	s_nop 0
	v_pk_add_f32 v[132:133], v[132:133], v[136:137] op_sel:[1,0] op_sel_hi:[0,1]
	v_mov_b32_e32 v135, v132
	v_pk_add_f32 v[138:139], v[134:135], v[140:141] neg_lo:[0,1] neg_hi:[0,1]
	v_mov_b32_e32 v131, v136
	v_sub_f32_e32 v133, v134, v138
	v_pk_add_f32 v[130:131], v[130:131], v[138:139] neg_lo:[0,1] neg_hi:[0,1]
	v_sub_f32_e32 v133, v140, v133
	v_add_f32_e32 v130, v130, v133
	v_add_f32_e32 v130, v130, v131
	v_add_f32_e32 v130, v132, v130
	v_cndmask_b32_e32 v130, v241, v130, vcc
	v_cmp_ngt_f32_e32 vcc, -1.0, v145
	v_mov_b32_e32 v131, 0x7fc00000
	s_nop 0
	v_cndmask_b32_e32 v130, v131, v130, vcc
	v_cmp_neq_f32_e32 vcc, -1.0, v145
	v_mov_b32_e32 v131, 0xff800000
	s_nop 0
	v_cndmask_b32_e32 v130, v131, v130, vcc
	v_cmp_lt_f32_e64 vcc, |v145|, s10
	v_add_u32_e32 v131, s43, v113
	s_addk_i32 s43, 0x200
	v_cndmask_b32_e32 v130, v130, v145, vcc
	v_sub_f32_e32 v130, v144, v130
	v_mul_f32_e32 v130, 0x3d800000, v130
	s_cmpk_eq_i32 s43, 0x2000
	ds_write_b32 v131, v130
	s_cbranch_scc0 .LBB0_2666
	s_waitcnt lgkmcnt(0)
	s_barrier
	s_and_saveexec_b64 vcc, s[4:5]
	s_cbranch_execz .LBB0_2670
	v_mov_b32_e32 v0, 0
	s_mov_b32 s43, 0
